# window loop: compact max3 row-max tree and K fragments read ahead of their MFMAs
# speedup vs baseline: 1.0391x; 1.0072x over previous
.LBB0_1358:
	s_lshl_b32 s42, s6, 14
	s_add_i32 s7, s42, 0
	v_add3_u32 v166, s7, v193, v194
	v_add_u32_e32 v162, v166, v195
	v_add_u32_e32 v163, v166, v196
	v_add_u32_e32 v164, v166, v197
	v_add_u32_e32 v165, v166, v198
	ds_read_b128 v[208:211], v162
	ds_read_b128 v[212:215], v162 offset:4096
	ds_read_b128 v[216:219], v163
	ds_read_b128 v[220:223], v163 offset:4096
	ds_read_b128 v[224:227], v164
	ds_read_b128 v[228:231], v164 offset:4096
	ds_read_b128 v[232:235], v165
	ds_read_b128 v[236:239], v165 offset:4096
	s_lshl_b32 s10, s80, 6
	s_sub_i32 s11, s54, s10
	s_cmpk_lt_i32 s11, 0x71
	s_cselect_b64 s[12:13], -1, 0
	s_sub_i32 s11, s81, s10
	s_cmpk_gt_i32 s11, 0x1ff
	s_cselect_b64 s[14:15], -1, 0
	s_or_b64 s[12:13], s[12:13], s[14:15]
	s_andn2_b64 vcc, exec, s[12:13]
	s_waitcnt lgkmcnt(7)
	v_mfma_f32_32x32x16_bf16 v[98:113], v[208:211], v[130:133], 0
	s_waitcnt lgkmcnt(6)
	v_mfma_f32_32x32x16_bf16 v[114:129], v[212:215], v[130:133], 0
	s_waitcnt lgkmcnt(5)
	v_mfma_f32_32x32x16_bf16 v[98:113], v[216:219], v[134:137], v[98:113]
	s_waitcnt lgkmcnt(4)
	v_mfma_f32_32x32x16_bf16 v[114:129], v[220:223], v[134:137], v[114:129]
	s_waitcnt lgkmcnt(3)
	v_mfma_f32_32x32x16_bf16 v[98:113], v[224:227], v[138:141], v[98:113]
	s_waitcnt lgkmcnt(2)
	v_mfma_f32_32x32x16_bf16 v[114:129], v[228:231], v[138:141], v[114:129]
	s_waitcnt lgkmcnt(1)
	v_mfma_f32_32x32x16_bf16 v[98:113], v[232:235], v[142:145], v[98:113]
	s_waitcnt lgkmcnt(0)
	v_mfma_f32_32x32x16_bf16 v[114:129], v[236:239], v[142:145], v[114:129]
	s_cbranch_vccnz .LBB0_1360
	v_or_b32_e32 v162, s10, v199
	v_sub_u32_e32 v207, v156, v162
	v_add_u32_e32 v222, -1, v207
	v_subrev_u32_e32 v223, 33, v207
	v_subrev_u32_e32 v224, 32, v207
	v_med3_i32 v162, v207, 0, v181
	v_med3_i32 v163, v222, 0, v181
	v_med3_i32 v164, v224, 0, v181
	v_med3_i32 v165, v223, 0, v181
	v_add_u32_e32 v225, -3, v207
	v_add_u32_e32 v226, -2, v207
	v_subrev_u32_e32 v227, 35, v207
	v_subrev_u32_e32 v228, 34, v207
	v_lshl_add_u32 v162, v162, 2, s5
	v_lshl_add_u32 v163, v163, 2, s5
	v_lshl_add_u32 v164, v164, 2, s5
	v_lshl_add_u32 v165, v165, 2, s5
	v_med3_i32 v166, v226, 0, v181
	v_med3_i32 v167, v225, 0, v181
	v_med3_i32 v168, v228, 0, v181
	v_med3_i32 v169, v227, 0, v181
	v_lshl_add_u32 v166, v166, 2, s5
	v_lshl_add_u32 v167, v167, 2, s5
	v_lshl_add_u32 v168, v168, 2, s5
	v_lshl_add_u32 v169, v169, 2, s5
	ds_read_b32 v178, v162
	ds_read_b32 v179, v163
	ds_read_b32 v164, v164
	ds_read_b32 v165, v165
	ds_read_b32 v208, v166
	ds_read_b32 v209, v167
	ds_read_b32 v162, v168
	ds_read_b32 v163, v169
	v_add_u32_e32 v229, -9, v207
	v_add_u32_e32 v230, -8, v207
	v_subrev_u32_e32 v231, 41, v207
	v_subrev_u32_e32 v232, 40, v207
	v_med3_i32 v166, v230, 0, v181
	v_med3_i32 v167, v229, 0, v181
	v_med3_i32 v168, v232, 0, v181
	v_med3_i32 v169, v231, 0, v181
	v_add_u32_e32 v233, -11, v207
	v_add_u32_e32 v234, -10, v207
	v_subrev_u32_e32 v235, 43, v207
	v_subrev_u32_e32 v236, 42, v207
	v_lshl_add_u32 v166, v166, 2, s5
	v_lshl_add_u32 v167, v167, 2, s5
	v_lshl_add_u32 v168, v168, 2, s5
	v_lshl_add_u32 v169, v169, 2, s5
	v_med3_i32 v170, v234, 0, v181
	v_med3_i32 v171, v233, 0, v181
	v_med3_i32 v172, v236, 0, v181
	v_med3_i32 v173, v235, 0, v181
	v_lshl_add_u32 v170, v170, 2, s5
	v_lshl_add_u32 v171, v171, 2, s5
	v_lshl_add_u32 v172, v172, 2, s5
	v_lshl_add_u32 v173, v173, 2, s5
	ds_read_b32 v210, v166
	ds_read_b32 v211, v167
	ds_read_b32 v168, v168
	ds_read_b32 v169, v169
	ds_read_b32 v212, v170
	ds_read_b32 v213, v171
	ds_read_b32 v166, v172
	ds_read_b32 v167, v173
	v_subrev_u32_e32 v237, 17, v207
	v_add_u32_e32 v238, -16, v207
	v_subrev_u32_e32 v239, 49, v207
	v_subrev_u32_e32 v240, 48, v207
	v_subrev_u32_e32 v244, 50, v207
	v_med3_i32 v170, v238, 0, v181
	v_med3_i32 v171, v237, 0, v181
	v_med3_i32 v172, v240, 0, v181
	v_med3_i32 v173, v239, 0, v181
	v_subrev_u32_e32 v241, 19, v207
	v_subrev_u32_e32 v242, 18, v207
	v_subrev_u32_e32 v243, 51, v207
	v_med3_i32 v214, v244, 0, v181
	v_lshl_add_u32 v170, v170, 2, s5
	v_lshl_add_u32 v171, v171, 2, s5
	v_lshl_add_u32 v172, v172, 2, s5
	v_lshl_add_u32 v173, v173, 2, s5
	v_med3_i32 v174, v242, 0, v181
	v_med3_i32 v175, v241, 0, v181
	v_lshl_add_u32 v218, v214, 2, s5
	v_med3_i32 v214, v243, 0, v181
	v_lshl_add_u32 v174, v174, 2, s5
	v_lshl_add_u32 v175, v175, 2, s5
	v_lshl_add_u32 v219, v214, 2, s5
	ds_read_b32 v214, v170
	ds_read_b32 v215, v171
	ds_read_b32 v172, v172
	ds_read_b32 v173, v173
	ds_read_b32 v216, v174
	ds_read_b32 v217, v175
	ds_read_b32 v170, v218
	ds_read_b32 v171, v219
	v_subrev_u32_e32 v246, 24, v207
	v_subrev_u32_e32 v247, 57, v207
	v_subrev_u32_e32 v250, 26, v207
	v_med3_i32 v174, v246, 0, v181
	v_med3_i32 v175, v247, 0, v181
	v_med3_i32 v220, v250, 0, v181
	v_subrev_u32_e32 v245, 25, v207
	v_lshl_add_u32 v174, v174, 2, s5
	v_subrev_u32_e32 v248, 56, v207
	v_lshl_add_u32 v175, v175, 2, s5
	v_subrev_u32_e32 v249, 27, v207
	v_lshl_add_u32 v220, v220, 2, s5
	v_cmp_gt_u32_e64 s[34:35], s53, v207
	s_waitcnt lgkmcnt(14)
	v_pk_add_f32 v[100:101], v[100:101], v[208:209]
	v_subrev_u32_e32 v208, 59, v207
	v_subrev_u32_e32 v207, 58, v207
	ds_read_b32 v218, v174
	ds_read_b32 v175, v175
	ds_read_b32 v220, v220
	v_med3_i32 v174, v245, 0, v181
	v_med3_i32 v221, v249, 0, v181
	v_pk_add_f32 v[98:99], v[98:99], v[178:179]
	v_med3_i32 v178, v207, 0, v181
	v_lshl_add_u32 v174, v174, 2, s5
	v_lshl_add_u32 v221, v221, 2, s5
	v_lshl_add_u32 v178, v178, 2, s5
	ds_read_b32 v219, v174
	ds_read_b32 v221, v221
	ds_read_b32 v178, v178
	v_med3_i32 v174, v248, 0, v181
	v_med3_i32 v179, v208, 0, v181
	v_lshl_add_u32 v174, v174, 2, s5
	v_lshl_add_u32 v179, v179, 2, s5
	ds_read_b32 v174, v174
	ds_read_b32 v179, v179
	v_cmp_gt_u32_e32 vcc, s53, v246
	v_cmp_gt_u32_e64 s[10:11], s53, v245
	v_cmp_gt_u32_e64 s[12:13], s53, v250
	v_cmp_gt_u32_e64 s[14:15], s53, v249
	v_cmp_gt_u32_e64 s[16:17], s53, v238
	v_cmp_gt_u32_e64 s[18:19], s53, v237
	v_cmp_gt_u32_e64 s[20:21], s53, v242
	v_cmp_gt_u32_e64 s[22:23], s53, v241
	v_cmp_gt_u32_e64 s[24:25], s53, v230
	v_cmp_gt_u32_e64 s[26:27], s53, v229
	v_cmp_gt_u32_e64 s[28:29], s53, v234
	v_cmp_gt_u32_e64 s[30:31], s53, v233
	v_cmp_gt_u32_e64 s[36:37], s53, v222
	v_cmp_gt_u32_e64 s[38:39], s53, v226
	v_cmp_gt_u32_e64 s[40:41], s53, v225
	s_waitcnt lgkmcnt(4)
	v_pk_add_f32 v[110:111], v[110:111], v[218:219]
	s_waitcnt lgkmcnt(3)
	v_pk_add_f32 v[112:113], v[112:113], v[220:221]
	v_pk_add_f32 v[106:107], v[106:107], v[214:215]
	v_pk_add_f32 v[108:109], v[108:109], v[216:217]
	v_pk_add_f32 v[102:103], v[102:103], v[210:211]
	v_pk_add_f32 v[104:105], v[104:105], v[212:213]
	v_cndmask_b32_e64 v101, v182, v101, s[40:41]
	v_cndmask_b32_e64 v100, v182, v100, s[38:39]
	v_cndmask_b32_e64 v99, v182, v99, s[36:37]
	v_cndmask_b32_e64 v98, v182, v98, s[34:35]
	v_cndmask_b32_e64 v105, v182, v105, s[30:31]
	v_cndmask_b32_e64 v104, v182, v104, s[28:29]
	v_cndmask_b32_e64 v103, v182, v103, s[26:27]
	v_cndmask_b32_e64 v102, v182, v102, s[24:25]
	v_cndmask_b32_e64 v109, v182, v109, s[22:23]
	v_cndmask_b32_e64 v108, v182, v108, s[20:21]
	v_cndmask_b32_e64 v107, v182, v107, s[18:19]
	v_cndmask_b32_e64 v106, v182, v106, s[16:17]
	v_cndmask_b32_e64 v113, v182, v113, s[14:15]
	v_cndmask_b32_e64 v112, v182, v112, s[12:13]
	v_cndmask_b32_e64 v111, v182, v111, s[10:11]
	v_cndmask_b32_e32 v110, v182, v110, vcc
	v_cmp_gt_u32_e32 vcc, s53, v248
	v_cmp_gt_u32_e64 s[10:11], s53, v247
	v_cmp_gt_u32_e64 s[12:13], s53, v207
	v_cmp_gt_u32_e64 s[14:15], s53, v208
	v_cmp_gt_u32_e64 s[16:17], s53, v240
	v_cmp_gt_u32_e64 s[18:19], s53, v239
	v_cmp_gt_u32_e64 s[20:21], s53, v244
	v_cmp_gt_u32_e64 s[22:23], s53, v243
	v_cmp_gt_u32_e64 s[24:25], s53, v232
	v_cmp_gt_u32_e64 s[26:27], s53, v231
	v_cmp_gt_u32_e64 s[28:29], s53, v236
	v_cmp_gt_u32_e64 s[30:31], s53, v235
	v_cmp_gt_u32_e64 s[34:35], s53, v224
	v_cmp_gt_u32_e64 s[36:37], s53, v223
	v_cmp_gt_u32_e64 s[38:39], s53, v228
	v_cmp_gt_u32_e64 s[40:41], s53, v227
	s_waitcnt lgkmcnt(1)
	v_pk_add_f32 v[126:127], v[126:127], v[174:175]
	s_waitcnt lgkmcnt(0)
	v_pk_add_f32 v[128:129], v[128:129], v[178:179]
	v_pk_add_f32 v[122:123], v[122:123], v[172:173]
	v_pk_add_f32 v[124:125], v[124:125], v[170:171]
	v_pk_add_f32 v[118:119], v[118:119], v[168:169]
	v_pk_add_f32 v[120:121], v[120:121], v[166:167]
	v_pk_add_f32 v[114:115], v[114:115], v[164:165]
	v_pk_add_f32 v[116:117], v[116:117], v[162:163]
	v_cndmask_b32_e64 v115, v182, v115, s[36:37]
	v_cndmask_b32_e64 v117, v182, v117, s[40:41]
	v_cndmask_b32_e64 v116, v182, v116, s[38:39]
	v_cndmask_b32_e64 v114, v182, v114, s[34:35]
	v_cndmask_b32_e64 v121, v182, v121, s[30:31]
	v_cndmask_b32_e64 v120, v182, v120, s[28:29]
	v_cndmask_b32_e64 v119, v182, v119, s[26:27]
	v_cndmask_b32_e64 v118, v182, v118, s[24:25]
	v_cndmask_b32_e64 v125, v182, v125, s[22:23]
	v_cndmask_b32_e64 v124, v182, v124, s[20:21]
	v_cndmask_b32_e64 v123, v182, v123, s[18:19]
	v_cndmask_b32_e64 v122, v182, v122, s[16:17]
	v_cndmask_b32_e64 v129, v182, v129, s[14:15]
	v_cndmask_b32_e64 v128, v182, v128, s[12:13]
	v_cndmask_b32_e64 v127, v182, v127, s[10:11]
	v_cndmask_b32_e32 v126, v182, v126, vcc
.LBB0_1360:
	s_ff1_i32_b64 s10, s[88:89]
	s_cmp_lg_u64 s[88:89], 0
	s_cselect_b32 s12, s10, -1
	s_nop 7
	v_max3_f32 v162, v98, v99, v100
	v_max3_f32 v163, v101, v102, v103
	v_max3_f32 v164, v104, v105, v106
	v_max3_f32 v165, v107, v108, v109
	v_max3_f32 v162, v162, v110, v111
	v_max3_f32 v163, v163, v112, v113
	v_max3_f32 v164, v164, v114, v115
	v_max3_f32 v165, v165, v116, v117
	v_max3_f32 v162, v162, v118, v119
	v_max3_f32 v163, v163, v120, v121
	v_max3_f32 v164, v164, v122, v123
	v_max3_f32 v165, v165, v124, v125
	v_max3_f32 v162, v162, v126, v127
	v_max3_f32 v163, v163, v128, v129
	v_max3_f32 v162, v162, v163, v164
	v_max_f32_e32 v162, v162, v165
	v_mov_b32_e32 v163, v162
	s_cmp_lt_i32 s12, 0
	s_nop 1
	v_permlane32_swap_b32 v162, v163
	s_cbranch_scc1 .LBB0_1362
	s_add_i32 s42, s42, 0xc000
	s_and_b32 s10, s42, 0xc000
	s_add_i32 s13, s10, 0
	s_lshl_b32 s10, s12, 6
	s_mul_i32 s11, s83, s10
	s_mul_hi_u32 s14, s82, s10
	s_add_i32 s11, s14, s11
	s_mul_i32 s10, s82, s10
	s_lshl_b64 s[10:11], s[10:11], 1
	v_lshl_add_u64 v[164:165], v[158:159], 0, s[10:11]
	s_add_i32 s13, s92, s13
	s_mov_b32 s14, m0
	s_mov_b32 m0, s13
	s_nop 0
	global_load_lds_dwordx4 v[164:165], off
	s_mov_b32 m0, s14
	v_lshl_add_u64 v[164:165], v[160:161], 0, s[10:11]
	s_addk_i32 s13, 0x2000
	s_mov_b32 s10, m0
	s_mov_b32 m0, s13
	s_nop 0
	global_load_lds_dwordx4 v[164:165], off
	s_mov_b32 m0, s10
